# P8 HID stores with sc0 sc1 nt cache policy
# speedup vs baseline: 1.0102x; 1.0055x over previous
.LBB0_877:
	s_cmp_eq_u32 s100, 0
	s_cbranch_scc1 .Ldhs8_idle
	s_cmp_lt_i32 s61, 6
	s_cbranch_scc0 .Ldhs8_hi
	s_cmp_lt_i32 s61, 2
	s_cbranch_scc0 .Ldhs8_q1
	s_cmp_lt_i32 s61, 0
	s_cbranch_scc0 .Ldhs8_g9
	global_store_dwordx4 v255, v[226:229], s[16:17] sc0 sc1 nt
	s_branch .Ldhs8_done
.Ldhs8_g9:
	global_store_dwordx4 v255, v[230:233], s[18:19] sc0 sc1 nt
	s_branch .Ldhs8_done
.Ldhs8_q1:
	s_cmp_lt_i32 s61, 4
	s_cbranch_scc0 .Ldhs8_g11
	global_store_dwordx4 v255, v[234:237], s[16:17] offset:1024 sc0 sc1 nt
	s_branch .Ldhs8_done
.Ldhs8_g11:
	global_store_dwordx4 v255, v[238:241], s[18:19] offset:1024 sc0 sc1 nt
	s_branch .Ldhs8_done
.Ldhs8_hi:
	s_cmp_lt_i32 s61, 10
	s_cbranch_scc0 .Ldhs8_q3
	s_cmp_lt_i32 s61, 8
	s_cbranch_scc0 .Ldhs8_g13
	global_store_dwordx4 v255, v[242:245], s[16:17] offset:2048 sc0 sc1 nt
	s_branch .Ldhs8_done
.Ldhs8_g13:
	global_store_dwordx4 v255, v[246:249], s[18:19] offset:2048 sc0 sc1 nt
	s_branch .Ldhs8_done
.Ldhs8_q3:
	s_cmp_lt_i32 s61, 12
	s_cbranch_scc0 .Ldhs8_g15
	global_store_dwordx4 v255, v[250:253], s[16:17] offset:3072 sc0 sc1 nt
	s_branch .Ldhs8_done
.Ldhs8_g15:
	global_store_dwordx4 v255, v[140:143], s[18:19] offset:3072 sc0 sc1 nt
	s_branch .Ldhs8_done

.LBB0_880:
	v_lshl_add_u32 v150, s34, 8, v144
	v_lshl_or_b32 v152, s56, 8, v146
	v_ashrrev_i32_e32 v151, 31, v150
	v_max_f32_e32 v124, 0, v124
	v_max_f32_e32 v120, 0, v120
	v_max_f32_e32 v125, 0, v125
	v_max_f32_e32 v121, 0, v121
	v_max_f32_e32 v126, 0, v126
	v_max_f32_e32 v127, 0, v127
	v_ashrrev_i32_e32 v153, 31, v152
	v_lshlrev_b64 v[154:155], 6, v[150:151]
	v_pk_mul_f32 v[124:125], v[124:125], v[124:125]
	v_pk_mul_f32 v[120:121], v[120:121], v[120:121]
	v_max_f32_e32 v122, 0, v122
	v_max_f32_e32 v123, 0, v123
	v_pk_mul_f32 v[126:127], v[126:127], v[126:127]
	v_pk_mul_f32 v[156:157], v[122:123], v[122:123]
	v_cvt_pk_bf16_f32 v122, v124, v125
	v_cvt_pk_bf16_f32 v123, v126, v127
	v_cvt_pk_bf16_f32 v124, v120, v121
	v_lshl_add_u64 v[120:121], s[78:79], 0, v[154:155]
	v_and_b32_e32 v126, 0xfe0, v152
	v_and_b32_e32 v127, 31, v152
	v_lshlrev_b32_e32 v126, 16, v126
	v_lshl_or_b32 v126, v127, 1, v126
	v_add_u32_e32 v255, v154, v126
	v_mov_b32_e32 v127, 0
	v_cvt_pk_bf16_f32 v125, v156, v157
	v_lshl_add_u64 v[120:121], v[120:121], 0, v[126:127]
	v_max_f32_e32 v112, 0, v112
	v_max_f32_e32 v113, 0, v113
	global_store_dwordx4 v[120:121], v[122:125], off sc0 sc1 nt
	s_nop 1
	v_pk_mul_f32 v[122:123], v[112:113], v[112:113]
	v_max_f32_e32 v114, 0, v114
	v_max_f32_e32 v116, 0, v116
	v_max_f32_e32 v117, 0, v117
	v_max_f32_e32 v112, 0, v118
	v_max_f32_e32 v113, 0, v119
	v_max_f32_e32 v115, 0, v115
	v_pk_mul_f32 v[116:117], v[116:117], v[116:117]
	v_pk_mul_f32 v[118:119], v[112:113], v[112:113]
	v_pk_mul_f32 v[124:125], v[114:115], v[114:115]
	v_cvt_pk_bf16_f32 v112, v116, v117
	v_cvt_pk_bf16_f32 v113, v118, v119
	v_cvt_pk_bf16_f32 v114, v122, v123
	v_cvt_pk_bf16_f32 v115, v124, v125
	v_max_f32_e32 v104, 0, v104
	v_max_f32_e32 v105, 0, v105
	v_lshl_add_u64 v[200:201], v[120:121], 0, s[98:99]
	global_store_dwordx4 v[200:201], v[112:115], off sc0 sc1 nt
	s_nop 1
	v_or_b32_e32 v112, 16, v150
	v_pk_mul_f32 v[114:115], v[104:105], v[104:105]
	v_ashrrev_i32_e32 v113, 31, v112
	v_max_f32_e32 v108, 0, v108
	v_max_f32_e32 v109, 0, v109
	v_max_f32_e32 v106, 0, v106
	v_lshlrev_b64 v[112:113], 6, v[112:113]
	v_pk_mul_f32 v[108:109], v[108:109], v[108:109]
	v_max_f32_e32 v104, 0, v110
	v_max_f32_e32 v105, 0, v111
	v_max_f32_e32 v107, 0, v107
	v_pk_mul_f32 v[110:111], v[104:105], v[104:105]
	v_pk_mul_f32 v[116:117], v[106:107], v[106:107]
	v_cvt_pk_bf16_f32 v104, v108, v109
	v_lshl_add_u64 v[108:109], s[78:79], 0, v[112:113]
	v_cvt_pk_bf16_f32 v105, v110, v111
	v_cvt_pk_bf16_f32 v106, v114, v115
	v_cvt_pk_bf16_f32 v107, v116, v117
	v_lshl_add_u64 v[108:109], v[108:109], 0, v[126:127]
	v_max_f32_e32 v96, 0, v96
	v_max_f32_e32 v97, 0, v97
	global_store_dwordx4 v[108:109], v[104:107], off sc0 sc1 nt
	s_nop 1
	v_pk_mul_f32 v[104:105], v[96:97], v[96:97]
	v_max_f32_e32 v98, 0, v98
	v_max_f32_e32 v100, 0, v100
	v_max_f32_e32 v101, 0, v101
	v_max_f32_e32 v96, 0, v102
	v_max_f32_e32 v97, 0, v103
	v_max_f32_e32 v99, 0, v99
	v_pk_mul_f32 v[100:101], v[100:101], v[100:101]
	v_pk_mul_f32 v[102:103], v[96:97], v[96:97]
	v_pk_mul_f32 v[106:107], v[98:99], v[98:99]
	v_cvt_pk_bf16_f32 v96, v100, v101
	v_cvt_pk_bf16_f32 v97, v102, v103
	v_cvt_pk_bf16_f32 v98, v104, v105
	v_cvt_pk_bf16_f32 v99, v106, v107
	v_max_f32_e32 v88, 0, v88
	v_max_f32_e32 v89, 0, v89
	v_lshl_add_u64 v[202:203], v[108:109], 0, s[98:99]
	global_store_dwordx4 v[202:203], v[96:99], off sc0 sc1 nt
	s_nop 1
	v_or_b32_e32 v96, 32, v150
	v_pk_mul_f32 v[98:99], v[88:89], v[88:89]
	v_ashrrev_i32_e32 v97, 31, v96
	v_max_f32_e32 v92, 0, v92
	v_max_f32_e32 v93, 0, v93
	v_max_f32_e32 v90, 0, v90
	v_lshlrev_b64 v[96:97], 6, v[96:97]
	v_pk_mul_f32 v[92:93], v[92:93], v[92:93]
	v_max_f32_e32 v88, 0, v94
	v_max_f32_e32 v89, 0, v95
	v_max_f32_e32 v91, 0, v91
	v_pk_mul_f32 v[94:95], v[88:89], v[88:89]
	v_pk_mul_f32 v[100:101], v[90:91], v[90:91]
	v_cvt_pk_bf16_f32 v88, v92, v93
	v_lshl_add_u64 v[92:93], s[78:79], 0, v[96:97]
	v_cvt_pk_bf16_f32 v89, v94, v95
	v_cvt_pk_bf16_f32 v90, v98, v99
	v_cvt_pk_bf16_f32 v91, v100, v101
	v_lshl_add_u64 v[92:93], v[92:93], 0, v[126:127]
	v_max_f32_e32 v80, 0, v80
	v_max_f32_e32 v81, 0, v81
	global_store_dwordx4 v[92:93], v[88:91], off sc0 sc1 nt
	s_nop 1
	v_pk_mul_f32 v[88:89], v[80:81], v[80:81]
	v_max_f32_e32 v82, 0, v82
	v_max_f32_e32 v84, 0, v84
	v_max_f32_e32 v85, 0, v85
	v_max_f32_e32 v80, 0, v86
	v_max_f32_e32 v81, 0, v87
	v_max_f32_e32 v83, 0, v83
	v_pk_mul_f32 v[84:85], v[84:85], v[84:85]
	v_pk_mul_f32 v[86:87], v[80:81], v[80:81]
	v_pk_mul_f32 v[90:91], v[82:83], v[82:83]
	v_cvt_pk_bf16_f32 v80, v84, v85
	v_cvt_pk_bf16_f32 v81, v86, v87
	v_cvt_pk_bf16_f32 v82, v88, v89
	v_cvt_pk_bf16_f32 v83, v90, v91
	v_max_f32_e32 v72, 0, v72
	v_max_f32_e32 v73, 0, v73
	v_lshl_add_u64 v[204:205], v[92:93], 0, s[98:99]
	global_store_dwordx4 v[204:205], v[80:83], off sc0 sc1 nt
	s_nop 1
	v_or_b32_e32 v80, 48, v150
	v_pk_mul_f32 v[82:83], v[72:73], v[72:73]
	v_ashrrev_i32_e32 v81, 31, v80
	v_max_f32_e32 v76, 0, v76
	v_max_f32_e32 v77, 0, v77
	v_max_f32_e32 v74, 0, v74
	v_lshlrev_b64 v[80:81], 6, v[80:81]
	v_pk_mul_f32 v[76:77], v[76:77], v[76:77]
	v_max_f32_e32 v72, 0, v78
	v_max_f32_e32 v73, 0, v79
	v_max_f32_e32 v75, 0, v75
	v_pk_mul_f32 v[78:79], v[72:73], v[72:73]
	v_pk_mul_f32 v[84:85], v[74:75], v[74:75]
	v_cvt_pk_bf16_f32 v72, v76, v77
	v_lshl_add_u64 v[76:77], s[78:79], 0, v[80:81]
	v_cvt_pk_bf16_f32 v73, v78, v79
	v_cvt_pk_bf16_f32 v74, v82, v83
	v_cvt_pk_bf16_f32 v75, v84, v85
	v_lshl_add_u64 v[76:77], v[76:77], 0, v[126:127]
	v_max_f32_e32 v64, 0, v64
	v_max_f32_e32 v65, 0, v65
	global_store_dwordx4 v[76:77], v[72:75], off sc0 sc1 nt
	s_nop 1
	v_pk_mul_f32 v[72:73], v[64:65], v[64:65]
	v_max_f32_e32 v66, 0, v66
	v_max_f32_e32 v68, 0, v68
	v_max_f32_e32 v69, 0, v69
	v_max_f32_e32 v64, 0, v70
	v_max_f32_e32 v65, 0, v71
	v_max_f32_e32 v67, 0, v67
	v_pk_mul_f32 v[68:69], v[68:69], v[68:69]
	v_pk_mul_f32 v[70:71], v[64:65], v[64:65]
	v_pk_mul_f32 v[74:75], v[66:67], v[66:67]
	v_cvt_pk_bf16_f32 v64, v68, v69
	v_cvt_pk_bf16_f32 v65, v70, v71
	v_cvt_pk_bf16_f32 v66, v72, v73
	v_cvt_pk_bf16_f32 v67, v74, v75
	v_max_f32_e32 v56, 0, v56
	v_max_f32_e32 v57, 0, v57
	v_lshl_add_u64 v[206:207], v[76:77], 0, s[98:99]
	global_store_dwordx4 v[206:207], v[64:67], off sc0 sc1 nt
	s_nop 1
	v_pk_mul_f32 v[64:65], v[56:57], v[56:57]
	v_max_f32_e32 v58, 0, v58
	v_max_f32_e32 v56, 0, v62
	v_max_f32_e32 v57, 0, v63
	v_max_f32_e32 v60, 0, v60
	v_max_f32_e32 v61, 0, v61
	v_max_f32_e32 v59, 0, v59
	v_pk_mul_f32 v[62:63], v[56:57], v[56:57]
	v_pk_mul_f32 v[60:61], v[60:61], v[60:61]
	v_pk_mul_f32 v[66:67], v[58:59], v[58:59]
	v_cvt_pk_bf16_f32 v227, v62, v63
	v_cvt_pk_bf16_f32 v226, v60, v61
	v_cvt_pk_bf16_f32 v228, v64, v65
	v_cvt_pk_bf16_f32 v229, v66, v67
	v_max_f32_e32 v48, 0, v48
	v_max_f32_e32 v49, 0, v49
	v_pk_mul_f32 v[56:57], v[48:49], v[48:49]
	v_max_f32_e32 v50, 0, v50
	v_max_f32_e32 v52, 0, v52
	v_max_f32_e32 v53, 0, v53
	v_max_f32_e32 v48, 0, v54
	v_max_f32_e32 v49, 0, v55
	v_max_f32_e32 v51, 0, v51
	v_pk_mul_f32 v[52:53], v[52:53], v[52:53]
	v_pk_mul_f32 v[54:55], v[48:49], v[48:49]
	v_pk_mul_f32 v[58:59], v[50:51], v[50:51]
	v_cvt_pk_bf16_f32 v230, v52, v53
	v_cvt_pk_bf16_f32 v231, v54, v55
	v_cvt_pk_bf16_f32 v232, v56, v57
	v_cvt_pk_bf16_f32 v233, v58, v59
	v_max_f32_e32 v40, 0, v40
	v_max_f32_e32 v41, 0, v41
	v_pk_mul_f32 v[48:49], v[40:41], v[40:41]
	v_max_f32_e32 v42, 0, v42
	v_max_f32_e32 v40, 0, v46
	v_max_f32_e32 v41, 0, v47
	v_max_f32_e32 v44, 0, v44
	v_max_f32_e32 v45, 0, v45
	v_max_f32_e32 v43, 0, v43
	v_pk_mul_f32 v[46:47], v[40:41], v[40:41]
	v_pk_mul_f32 v[44:45], v[44:45], v[44:45]
	v_pk_mul_f32 v[50:51], v[42:43], v[42:43]
	v_cvt_pk_bf16_f32 v235, v46, v47
	v_cvt_pk_bf16_f32 v234, v44, v45
	v_cvt_pk_bf16_f32 v236, v48, v49
	v_cvt_pk_bf16_f32 v237, v50, v51
	v_max_f32_e32 v32, 0, v32
	v_max_f32_e32 v33, 0, v33
	v_pk_mul_f32 v[40:41], v[32:33], v[32:33]
	v_max_f32_e32 v34, 0, v34
	v_max_f32_e32 v36, 0, v36
	v_max_f32_e32 v37, 0, v37
	v_max_f32_e32 v32, 0, v38
	v_max_f32_e32 v33, 0, v39
	v_max_f32_e32 v35, 0, v35
	v_pk_mul_f32 v[36:37], v[36:37], v[36:37]
	v_pk_mul_f32 v[38:39], v[32:33], v[32:33]
	v_pk_mul_f32 v[42:43], v[34:35], v[34:35]
	v_cvt_pk_bf16_f32 v238, v36, v37
	v_cvt_pk_bf16_f32 v239, v38, v39
	v_cvt_pk_bf16_f32 v240, v40, v41
	v_cvt_pk_bf16_f32 v241, v42, v43
	v_max_f32_e32 v24, 0, v24
	v_max_f32_e32 v25, 0, v25
	v_pk_mul_f32 v[32:33], v[24:25], v[24:25]
	v_max_f32_e32 v26, 0, v26
	v_max_f32_e32 v24, 0, v30
	v_max_f32_e32 v25, 0, v31
	v_max_f32_e32 v28, 0, v28
	v_max_f32_e32 v29, 0, v29
	v_max_f32_e32 v27, 0, v27
	v_pk_mul_f32 v[30:31], v[24:25], v[24:25]
	v_pk_mul_f32 v[28:29], v[28:29], v[28:29]
	v_pk_mul_f32 v[34:35], v[26:27], v[26:27]
	v_cvt_pk_bf16_f32 v243, v30, v31
	v_cvt_pk_bf16_f32 v242, v28, v29
	v_cvt_pk_bf16_f32 v244, v32, v33
	v_cvt_pk_bf16_f32 v245, v34, v35
	v_max_f32_e32 v16, 0, v16
	v_max_f32_e32 v17, 0, v17
	v_pk_mul_f32 v[24:25], v[16:17], v[16:17]
	v_max_f32_e32 v18, 0, v18
	v_max_f32_e32 v20, 0, v20
	v_max_f32_e32 v21, 0, v21
	v_max_f32_e32 v16, 0, v22
	v_max_f32_e32 v17, 0, v23
	v_max_f32_e32 v19, 0, v19
	v_pk_mul_f32 v[20:21], v[20:21], v[20:21]
	v_pk_mul_f32 v[22:23], v[16:17], v[16:17]
	v_pk_mul_f32 v[26:27], v[18:19], v[18:19]
	v_cvt_pk_bf16_f32 v246, v20, v21
	v_cvt_pk_bf16_f32 v247, v22, v23
	v_cvt_pk_bf16_f32 v248, v24, v25
	v_cvt_pk_bf16_f32 v249, v26, v27
	v_max_f32_e32 v8, 0, v8
	v_max_f32_e32 v9, 0, v9
	v_pk_mul_f32 v[16:17], v[8:9], v[8:9]
	v_max_f32_e32 v10, 0, v10
	v_max_f32_e32 v8, 0, v14
	v_max_f32_e32 v9, 0, v15
	v_max_f32_e32 v12, 0, v12
	v_max_f32_e32 v13, 0, v13
	v_max_f32_e32 v11, 0, v11
	v_pk_mul_f32 v[14:15], v[8:9], v[8:9]
	v_pk_mul_f32 v[12:13], v[12:13], v[12:13]
	v_pk_mul_f32 v[18:19], v[10:11], v[10:11]
	v_cvt_pk_bf16_f32 v251, v14, v15
	v_cvt_pk_bf16_f32 v250, v12, v13
	v_cvt_pk_bf16_f32 v252, v16, v17
	v_cvt_pk_bf16_f32 v253, v18, v19
	v_max_f32_e32 v0, 0, v0
	v_max_f32_e32 v1, 0, v1
	v_pk_mul_f32 v[8:9], v[0:1], v[0:1]
	v_max_f32_e32 v2, 0, v2
	v_max_f32_e32 v4, 0, v4
	v_max_f32_e32 v5, 0, v5
	v_max_f32_e32 v0, 0, v6
	v_max_f32_e32 v1, 0, v7
	v_max_f32_e32 v3, 0, v3
	v_pk_mul_f32 v[4:5], v[4:5], v[4:5]
	v_pk_mul_f32 v[6:7], v[0:1], v[0:1]
	v_pk_mul_f32 v[10:11], v[2:3], v[2:3]
	v_cvt_pk_bf16_f32 v140, v4, v5
	v_cvt_pk_bf16_f32 v141, v6, v7
	v_cvt_pk_bf16_f32 v142, v8, v9
	v_cvt_pk_bf16_f32 v143, v10, v11
	s_andn2_b64 vcc, exec, s[4:5]
	s_mov_b64 s[4:5], -1
	s_mov_b32 s100, 1
	s_cbranch_vccnz .LBB0_869
	s_andn2_b64 vcc, exec, s[6:7]
	s_cbranch_vccnz .LBB0_868
	s_barrier
	s_branch .LBB0_868
.LBB0_883:
	global_store_dwordx4 v255, v[226:229], s[16:17] sc0 sc1 nt
	global_store_dwordx4 v255, v[230:233], s[18:19] sc0 sc1 nt
	global_store_dwordx4 v255, v[234:237], s[16:17] offset:1024 sc0 sc1 nt
	global_store_dwordx4 v255, v[238:241], s[18:19] offset:1024 sc0 sc1 nt
	global_store_dwordx4 v255, v[242:245], s[16:17] offset:2048 sc0 sc1 nt
	global_store_dwordx4 v255, v[246:249], s[18:19] offset:2048 sc0 sc1 nt
	global_store_dwordx4 v255, v[250:253], s[16:17] offset:3072 sc0 sc1 nt
	global_store_dwordx4 v255, v[140:143], s[18:19] offset:3072 sc0 sc1 nt
	s_waitcnt vmcnt(0)
	s_barrier
